# tile-loop bound tests on the scalar unit (s_cmp/s_cselect) instead of two 64-bit VALU compares per tile, in the four GEMM tile loops
# baseline (speedup 1.0000x reference)
;     __host__ __device__ bool next(int i, Unit& u) const {
;         const long L = (long)i * G + c; if (L >= nwg) return false;
;         int wgid = (int)L; { const int q = nwg / NXCD, r = nwg % NXCD, xcd = wgid % NXCD, off = wgid / NXCD; wgid = (xcd < r ? xcd * (q + 1) : r * (q + 1) + (xcd - r) * q) + off; }
;         const int nig = WGM * nN, gid = wgid / nig, fm = gid * WGM, gsz = (nM - fm) < WGM ? (nM - fm) : WGM;
;         u.pm = fm + ((wgid % nig) % gsz); u.pn = (wgid % nig) / gsz; return true;
; template <class Epi, class Sched, bool ALIGN_EPI = false, bool SP2 = false>
; __device__ __forceinline__ void gemm_phase(PG8_LAS unsigned char* lds, const Gemm g, const Sched& S, const Epi& E) {
;     ...
;         const bool has_next = S.next(ui + 1, nxt);
;         const char* nA = has_next ? (const char*)g.A + (size_t)nxt.pm * tstepA : cA; const char* nB = has_next ? (const char*)g.Bt + (size_t)nxt.pn * tstepB : cB;
.LBB0_158:
	s_add_i32 s53, s53, 1
	v_readlane_b32 s2, v253, 5
	s_mul_i32 s2, s53, s2
	s_mul_hi_u32 s3, s53, s33
	s_add_i32 s3, s3, s2
	s_mul_i32 s2, s53, s33
	v_readlane_b32 s8, v254, 21
	v_readlane_b32 s9, v254, 22
	s_add_u32 s12, s2, s8
	s_addc_u32 s13, s3, s9
	s_mov_b32 s7, s31
	s_cmp_lt_u32 s12, 0x600
	s_cselect_b64 s[30:31], -1, 0
	s_mov_b32 s16, s49
	s_cbranch_scc0 .LBB0_160
	s_lshr_b32 s3, s12, 3
	s_and_b32 s2, s12, 7
	s_mulk_i32 s2, 0xc0
	s_add_i32 s2, s2, s3
	s_mul_hi_i32 s3, s2, 0x2aaaaaab
	s_lshr_b32 s8, s3, 31
	s_ashr_i32 s3, s3, 4
	s_add_i32 s3, s3, s8
	s_lshl_b32 s8, s3, 3
	s_mulk_i32 s3, 0x60
	s_sub_i32 s2, s2, s3
	s_ashr_i32 s48, s2, 3
	s_and_b32 s2, s2, 7
	s_add_i32 s54, s8, s2

;     __host__ __device__ bool next(int i, Unit& u) const {
;         const long L = (long)i * G + c; if (L >= nwg) return false;
;         int wgid = (int)L; { const int q = nwg / NXCD, r = nwg % NXCD, xcd = wgid % NXCD, off = wgid / NXCD; wgid = (xcd < r ? xcd * (q + 1) : r * (q + 1) + (xcd - r) * q) + off; }
;         const int nig = WGM * nN, gid = wgid / nig, fm = gid * WGM, gsz = (nM - fm) < WGM ? (nM - fm) : WGM;
;         u.pm = fm + ((wgid % nig) % gsz); u.pn = (wgid % nig) / gsz; return true;
; template <class Epi, class Sched, bool ALIGN_EPI = false, bool SP2 = false>
; __device__ __forceinline__ void gemm_phase(PG8_LAS unsigned char* lds, const Gemm g, const Sched& S, const Epi& E) {
;     ...
;         const bool has_next = S.next(ui + 1, nxt);
;         const char* nA = has_next ? (const char*)g.A + (size_t)nxt.pm * tstepA : cA; const char* nB = has_next ? (const char*)g.Bt + (size_t)nxt.pn * tstepB : cB;
.LBB0_247:
	s_add_i32 s97, s97, 1
	v_readlane_b32 s2, v253, 5
	s_mul_i32 s2, s97, s2
	s_mul_hi_u32 s3, s97, s33
	s_add_i32 s3, s3, s2
	s_mul_i32 s2, s97, s33
	v_readlane_b32 s12, v254, 21
	v_readlane_b32 s13, v254, 22
	s_add_u32 s28, s2, s12
	s_addc_u32 s29, s3, s13
	s_cmp_lt_u32 s28, 0x600
	s_cselect_b64 s[40:41], -1, 0
	s_cbranch_scc0 .LBB0_249
	s_lshr_b32 s3, s28, 3
	s_and_b32 s2, s28, 7
	s_mulk_i32 s2, 0xc0
	s_add_i32 s2, s2, s3
	s_mul_hi_i32 s3, s2, 0x2aaaaaab
	s_lshr_b32 s11, s3, 31
	s_ashr_i32 s3, s3, 4
	s_add_i32 s3, s3, s11
	s_lshl_b32 s11, s3, 3
	s_mulk_i32 s3, 0x60
	s_sub_i32 s2, s2, s3
	s_ashr_i32 s46, s2, 3
	s_and_b32 s2, s2, 7
	s_add_i32 s48, s11, s2

;     __host__ __device__ bool next(int i, Unit& u) const {
;         const long L = (long)i * G + c; if (L >= nwg) return false;
;         int wgid = (int)L; { const int q = nwg / NXCD, r = nwg % NXCD, xcd = wgid % NXCD, off = wgid / NXCD; wgid = (xcd < r ? xcd * (q + 1) : r * (q + 1) + (xcd - r) * q) + off; }
;         const int nig = WGM * nN, gid = wgid / nig, fm = gid * WGM, gsz = (nM - fm) < WGM ? (nM - fm) : WGM;
;         u.pm = fm + ((wgid % nig) % gsz); u.pn = (wgid % nig) / gsz; return true;
; template <class Epi, class Sched, bool ALIGN_EPI = false, bool SP2 = false>
; __device__ __forceinline__ void gemm_phase(PG8_LAS unsigned char* lds, const Gemm g, const Sched& S, const Epi& E) {
;     ...
;         const bool has_next = S.next(ui + 1, nxt);
;         const char* nA = has_next ? (const char*)g.A + (size_t)nxt.pm * tstepA : cA; const char* nB = has_next ? (const char*)g.Bt + (size_t)nxt.pn * tstepB : cB;
.LBB0_334:
	s_add_i32 s99, s99, 1
	v_readlane_b32 s0, v253, 5
	s_mul_i32 s0, s99, s0
	s_mul_hi_u32 s1, s99, s33
	s_add_i32 s1, s1, s0
	s_mul_i32 s0, s99, s33
	v_readlane_b32 s2, v254, 21
	v_readlane_b32 s3, v254, 22
	s_add_u32 s12, s0, s2
	s_addc_u32 s13, s1, s3
	s_cmp_lt_u32 s12, 0x200
	s_cselect_b64 s[0:1], -1, 0
	s_cbranch_scc0 .LBB0_340
	s_ashr_i32 s2, s12, 31
	s_lshr_b32 s2, s2, 29
	s_add_i32 s2, s12, s2
	s_and_b32 s3, s2, -8
	s_sub_i32 s3, s12, s3
	s_cmp_gt_i32 s3, -1
	s_mov_b64 s[12:13], -1
	s_cbranch_scc0 .LBB0_337
	s_lshl_b32 s7, s3, 6
	s_mov_b64 s[12:13], 0

;     __host__ __device__ bool next(int i, Unit& u) const {
;         const long L = (long)i * G + c; if (L >= nwg) return false;
;         int wgid = (int)L; { const int q = nwg / NXCD, r = nwg % NXCD, xcd = wgid % NXCD, off = wgid / NXCD; wgid = (xcd < r ? xcd * (q + 1) : r * (q + 1) + (xcd - r) * q) + off; }
;         const int nig = WGM * nN, gid = wgid / nig, fm = gid * WGM, gsz = (nM - fm) < WGM ? (nM - fm) : WGM;
;         u.pm = fm + ((wgid % nig) % gsz); u.pn = (wgid % nig) / gsz; return true;
; template <class Epi, class Sched, bool ALIGN_EPI = false, bool SP2 = false>
; __device__ __forceinline__ void gemm_phase(PG8_LAS unsigned char* lds, const Gemm g, const Sched& S, const Epi& E) {
;     ...
;         const bool has_next = S.next(ui + 1, nxt);
;         const char* nA = has_next ? (const char*)g.A + (size_t)nxt.pm * tstepA : cA; const char* nB = has_next ? (const char*)g.Bt + (size_t)nxt.pn * tstepB : cB;
.LBB0_475:
	s_add_i32 s54, s54, 1
	v_readlane_b32 s2, v253, 5
	s_mul_i32 s2, s54, s2
	s_mul_hi_u32 s3, s54, s33
	s_add_i32 s3, s3, s2
	s_mul_i32 s2, s54, s33
	v_readlane_b32 s10, v254, 21
	v_readlane_b32 s11, v254, 22
	s_add_u32 s28, s2, s10
	s_addc_u32 s29, s3, s11
	s_cmp_lt_u32 s28, 0xb00
	s_cselect_b64 s[40:41], -1, 0
	s_cbranch_scc0 .LBB0_477
	s_lshr_b32 s3, s28, 3
	s_and_b32 s2, s28, 7
	s_mulk_i32 s2, 0x160
	s_add_i32 s2, s2, s3
	s_mul_hi_i32 s3, s2, 0x2e8ba2e9
	s_lshr_b32 s10, s3, 31
	s_ashr_i32 s3, s3, 5
	s_add_i32 s3, s3, s10
	s_lshl_b32 s10, s3, 3
	s_mulk_i32 s3, 0xb0
	s_sub_i32 s2, s2, s3
	s_ashr_i32 s24, s2, 3
	s_and_b32 s2, s2, 7
	s_add_i32 s26, s10, s2
